# combined variant plus MLA next-tile prefetch block moved from the segment heads into the shadow of the first QK MFMAs
# baseline (speedup 1.0000x reference)
.LBB0_543:
	ds_read_b128 v[32:35], v105
	ds_read_b128 v[132:135], v105 offset:32
	ds_read_b128 v[48:51], v105 offset:6656
	ds_read_b128 v[136:139], v105 offset:6688
	ds_read_b128 v[140:143], v105 offset:64
	ds_read_b128 v[146:149], v105 offset:96
	ds_read_b128 v[152:155], v105 offset:6720
	ds_read_b128 v[156:159], v105 offset:6752
	ds_read_b128 v[160:163], v105 offset:128
	ds_read_b128 v[164:167], v105 offset:160
	ds_read_b128 v[168:171], v105 offset:6784
	ds_read_b128 v[172:175], v105 offset:6816
	s_waitcnt lgkmcnt(11)
	v_mfma_f32_32x32x16_bf16 v[32:47], v[32:35], v[64:67], 0
	s_waitcnt lgkmcnt(9)
	v_mfma_f32_32x32x16_bf16 v[48:63], v[48:51], v[64:67], 0
	s_and_b64 vcc, exec, s[4:5]
	s_cbranch_vccnz .Lmla_pf0_skip
	v_ashrrev_i32_e32 v121, 31, v120
	v_lshlrev_b64 v[206:207], 10, v[120:121]
	v_lshl_add_u64 v[206:207], v[118:119], 0, v[206:207]
	global_load_dwordx4 v[88:91], v[206:207], off
	global_load_dwordx4 v[92:95], v[206:207], off offset:128
	v_mad_i64_i32 v[206:207], s[14:15], v120, s3, v[108:109]
	global_load_dwordx2 v[116:117], v[206:207], off
.Lmla_pf0_skip:
	v_mfma_f32_32x32x16_bf16 v[32:47], v[132:135], v[68:71], v[32:47]
	s_waitcnt lgkmcnt(8)
	v_mfma_f32_32x32x16_bf16 v[48:63], v[136:139], v[68:71], v[48:63]
	s_waitcnt lgkmcnt(7)
	v_mfma_f32_32x32x16_bf16 v[32:47], v[140:143], v[72:75], v[32:47]
	s_waitcnt lgkmcnt(5)
	v_mfma_f32_32x32x16_bf16 v[48:63], v[152:155], v[72:75], v[48:63]
	v_mfma_f32_32x32x16_bf16 v[32:47], v[146:149], v[76:79], v[32:47]
	s_waitcnt lgkmcnt(4)
	v_mfma_f32_32x32x16_bf16 v[48:63], v[156:159], v[76:79], v[48:63]
	s_waitcnt lgkmcnt(3)
	v_mfma_f32_32x32x16_bf16 v[32:47], v[160:163], v[80:83], v[32:47]
	s_waitcnt lgkmcnt(1)
	v_mfma_f32_32x32x16_bf16 v[48:63], v[168:171], v[80:83], v[48:63]
	v_mfma_f32_32x32x16_bf16 v[32:47], v[164:167], v[84:87], v[32:47]
	s_waitcnt lgkmcnt(0)
	v_mfma_f32_32x32x16_bf16 v[48:63], v[172:175], v[84:87], v[48:63]
	s_nop 9
	v_exp_f32_e32 v121, v32
	v_exp_f32_e32 v125, v33
	v_exp_f32_e32 v126, v34
	v_exp_f32_e32 v127, v35
	v_exp_f32_e32 v131, v36
	v_exp_f32_e32 v132, v37
	v_exp_f32_e32 v133, v38
	v_exp_f32_e32 v135, v48
	v_exp_f32_e32 v136, v49
	v_exp_f32_e32 v137, v50
	v_exp_f32_e32 v138, v51
	v_exp_f32_e32 v139, v52
	v_exp_f32_e32 v140, v53
	v_exp_f32_e32 v141, v54
	v_exp_f32_e32 v134, v39
	v_exp_f32_e32 v142, v55
	v_exp_f32_e32 v143, v40
	v_exp_f32_e32 v158, v56
	v_exp_f32_e32 v144, v41
	v_exp_f32_e32 v159, v57
	v_exp_f32_e32 v152, v42
	v_exp_f32_e32 v160, v58
	v_exp_f32_e32 v153, v43
	v_exp_f32_e32 v161, v59
	v_exp_f32_e32 v154, v44
	v_exp_f32_e32 v162, v60
	v_exp_f32_e32 v155, v45
	v_exp_f32_e32 v163, v61
	v_exp_f32_e32 v156, v46
	v_exp_f32_e32 v164, v62
	v_exp_f32_e32 v157, v47
	v_exp_f32_e32 v165, v63
	ds_read_b64_tr_b16 v[32:33], v218 offset:13312
	ds_read_b64_tr_b16 v[34:35], v218 offset:14336
	ds_read_b64_tr_b16 v[38:39], v218 offset:14592
	ds_read_b64_tr_b16 v[36:37], v218 offset:13568
	ds_read_b64_tr_b16 v[40:41], v218 offset:15360
	ds_read_b64_tr_b16 v[42:43], v218 offset:16384
	ds_read_b64_tr_b16 v[46:47], v218 offset:16640
	ds_read_b64_tr_b16 v[44:45], v218 offset:15616
	ds_read_b64_tr_b16 v[48:49], v218 offset:17408
	ds_read_b64_tr_b16 v[50:51], v218 offset:18432
	ds_read_b64_tr_b16 v[54:55], v218 offset:18688
	ds_read_b64_tr_b16 v[52:53], v218 offset:17664
	ds_read_b64_tr_b16 v[56:57], v218 offset:19456
	ds_read_b64_tr_b16 v[58:59], v218 offset:20480
	ds_read_b64_tr_b16 v[62:63], v218 offset:20736
	ds_read_b64_tr_b16 v[60:61], v218 offset:19712
	v_cvt_pk_bf16_f32 v146, v121, v125
	v_cvt_pk_bf16_f32 v147, v126, v127
	v_cvt_pk_bf16_f32 v148, v131, v132
	v_cvt_pk_bf16_f32 v149, v133, v134
	s_add_i32 s13, s12, 1
	s_waitcnt lgkmcnt(14)
	v_mfma_f32_32x32x16_bf16 v[16:31], v[32:35], v[146:149], v[16:31]
	v_cvt_pk_bf16_f32 v32, v135, v136
	v_cvt_pk_bf16_f32 v33, v137, v138
	v_cvt_pk_bf16_f32 v34, v139, v140
	v_cvt_pk_bf16_f32 v35, v141, v142
	s_cmp_ge_u32 s13, s31
	s_waitcnt lgkmcnt(12)
	v_mfma_f32_32x32x16_bf16 v[0:15], v[36:39], v[146:149], v[0:15]
	v_cvt_pk_bf16_f32 v36, v143, v144
	v_cvt_pk_bf16_f32 v37, v152, v153
	v_cvt_pk_bf16_f32 v38, v154, v155
	v_cvt_pk_bf16_f32 v39, v156, v157
	s_waitcnt lgkmcnt(10)
	v_mfma_f32_32x32x16_bf16 v[16:31], v[40:43], v[36:39], v[16:31]
	s_waitcnt lgkmcnt(8)
	v_mfma_f32_32x32x16_bf16 v[0:15], v[44:47], v[36:39], v[0:15]
	s_waitcnt lgkmcnt(6)
	v_mfma_f32_32x32x16_bf16 v[16:31], v[48:51], v[32:35], v[16:31]
	s_waitcnt lgkmcnt(4)
	v_mfma_f32_32x32x16_bf16 v[0:15], v[52:55], v[32:35], v[0:15]
	v_cvt_pk_bf16_f32 v32, v158, v159
	v_cvt_pk_bf16_f32 v33, v160, v161
	v_cvt_pk_bf16_f32 v34, v162, v163
	v_cvt_pk_bf16_f32 v35, v164, v165
	s_waitcnt lgkmcnt(2)
	v_mfma_f32_32x32x16_bf16 v[16:31], v[56:59], v[32:35], v[16:31]
	s_waitcnt lgkmcnt(0)
	v_mfma_f32_32x32x16_bf16 v[0:15], v[60:63], v[32:35], v[0:15]
	s_cbranch_scc1 .LBB0_545
	s_cmp_ge_u32 s11, s31
	s_cbranch_scc1 .Lmla_w0_tail
	s_waitcnt vmcnt(5)
	ds_write_b128 v220, v[96:99] offset:21504
	s_waitcnt vmcnt(4)
	ds_write_b128 v219, v[100:103] offset:34816
	s_waitcnt vmcnt(3)
	ds_write_b64 v129, v[114:115] offset:21632
	s_branch .LBB0_545

.LBB0_547:
	ds_read_b128 v[32:35], v105 offset:21504
	ds_read_b128 v[146:149], v105 offset:21536
	ds_read_b128 v[48:51], v105 offset:28160
	ds_read_b128 v[166:169], v105 offset:28192
	ds_read_b128 v[170:173], v105 offset:21568
	ds_read_b128 v[174:177], v105 offset:21600
	ds_read_b128 v[178:181], v105 offset:28224
	ds_read_b128 v[182:185], v105 offset:28256
	ds_read_b128 v[186:189], v105 offset:21632
	ds_read_b128 v[190:193], v105 offset:21664
	ds_read_b128 v[194:197], v105 offset:28288
	ds_read_b128 v[198:201], v105 offset:28320
	s_waitcnt lgkmcnt(11)
	v_mfma_f32_32x32x16_bf16 v[32:47], v[32:35], v[64:67], 0
	v_add_f32_e32 v226, v121, v125
	v_add_f32_e32 v227, v135, v136
	v_add_f32_e32 v226, v126, v226
	s_waitcnt lgkmcnt(9)
	v_mfma_f32_32x32x16_bf16 v[48:63], v[48:51], v[64:67], 0
	s_cmp_ge_u32 s12, s10
	s_cbranch_scc1 .Lmla_pf1_skip
	v_add_u32_e32 v206, 64, v120
	v_ashrrev_i32_e32 v207, 31, v206
	v_lshlrev_b64 v[208:209], 10, v[206:207]
	v_lshl_add_u64 v[208:209], v[118:119], 0, v[208:209]
	v_mad_i64_i32 v[206:207], s[12:13], v206, s3, v[108:109]
	global_load_dwordx4 v[96:99], v[208:209], off
	global_load_dwordx4 v[100:103], v[208:209], off offset:128
	global_load_dwordx2 v[114:115], v[206:207], off
.Lmla_pf1_skip:
	v_add_f32_e32 v227, v137, v227
	v_add_f32_e32 v226, v127, v226
	v_add_f32_e32 v227, v138, v227
	v_mfma_f32_32x32x16_bf16 v[32:47], v[146:149], v[68:71], v[32:47]
	v_add_f32_e32 v226, v131, v226
	v_add_f32_e32 v227, v139, v227
	v_add_f32_e32 v226, v132, v226
	s_waitcnt lgkmcnt(8)
	v_mfma_f32_32x32x16_bf16 v[48:63], v[166:169], v[68:71], v[48:63]
	v_add_f32_e32 v227, v140, v227
	v_add_f32_e32 v226, v133, v226
	v_add_f32_e32 v227, v141, v227
	s_waitcnt lgkmcnt(7)
	v_mfma_f32_32x32x16_bf16 v[32:47], v[170:173], v[72:75], v[32:47]
	v_add_f32_e32 v226, v134, v226
	v_add_f32_e32 v227, v142, v227
	v_add_f32_e32 v226, v143, v226
	s_waitcnt lgkmcnt(5)
	v_mfma_f32_32x32x16_bf16 v[48:63], v[178:181], v[72:75], v[48:63]
	v_add_f32_e32 v227, v158, v227
	v_add_f32_e32 v226, v144, v226
	v_add_f32_e32 v227, v159, v227
	v_mfma_f32_32x32x16_bf16 v[32:47], v[174:177], v[76:79], v[32:47]
	v_add_f32_e32 v226, v152, v226
	v_add_f32_e32 v227, v160, v227
	v_add_f32_e32 v226, v153, v226
	s_waitcnt lgkmcnt(4)
	v_mfma_f32_32x32x16_bf16 v[48:63], v[182:185], v[76:79], v[48:63]
	v_add_f32_e32 v227, v161, v227
	v_add_f32_e32 v226, v154, v226
	v_add_f32_e32 v227, v162, v227
	s_waitcnt lgkmcnt(3)
	v_mfma_f32_32x32x16_bf16 v[32:47], v[186:189], v[80:83], v[32:47]
	v_add_f32_e32 v226, v155, v226
	v_add_f32_e32 v227, v163, v227
	v_add_f32_e32 v226, v156, v226
	s_waitcnt lgkmcnt(1)
	v_mfma_f32_32x32x16_bf16 v[48:63], v[194:197], v[80:83], v[48:63]
	v_add_f32_e32 v227, v164, v227
	v_add_f32_e32 v226, v157, v226
	v_add_f32_e32 v227, v165, v227
	v_mfma_f32_32x32x16_bf16 v[32:47], v[190:193], v[84:87], v[32:47]
	v_add_f32_e32 v226, v226, v227
	s_waitcnt lgkmcnt(0)
	v_mfma_f32_32x32x16_bf16 v[48:63], v[198:201], v[84:87], v[48:63]
	s_nop 9
	v_exp_f32_e32 v32, v32
	v_exp_f32_e32 v33, v33
	v_exp_f32_e32 v34, v34
	v_exp_f32_e32 v35, v35
	v_exp_f32_e32 v36, v36
	v_exp_f32_e32 v37, v37
	v_exp_f32_e32 v38, v38
	v_exp_f32_e32 v48, v48
	v_exp_f32_e32 v49, v49
	v_exp_f32_e32 v50, v50
	v_exp_f32_e32 v51, v51
	v_exp_f32_e32 v52, v52
	v_exp_f32_e32 v53, v53
	v_exp_f32_e32 v54, v54
	v_exp_f32_e32 v39, v39
	v_exp_f32_e32 v55, v55
	v_exp_f32_e32 v40, v40
	v_exp_f32_e32 v56, v56
	v_exp_f32_e32 v41, v41
	v_exp_f32_e32 v57, v57
	v_exp_f32_e32 v42, v42
	v_exp_f32_e32 v58, v58
	v_exp_f32_e32 v43, v43
	v_exp_f32_e32 v59, v59
	v_exp_f32_e32 v44, v44
	v_exp_f32_e32 v60, v60
	v_exp_f32_e32 v45, v45
	v_exp_f32_e32 v61, v61
	v_exp_f32_e32 v46, v46
	v_exp_f32_e32 v62, v62
	v_exp_f32_e32 v47, v47
	v_exp_f32_e32 v63, v63
	ds_read_b64_tr_b16 v[146:147], v218 offset:34816
	ds_read_b64_tr_b16 v[148:149], v218 offset:35840
	ds_read_b64_tr_b16 v[168:169], v218 offset:36096
	ds_read_b64_tr_b16 v[166:167], v218 offset:35072
	ds_read_b64_tr_b16 v[170:171], v218 offset:36864
	ds_read_b64_tr_b16 v[172:173], v218 offset:37888
	ds_read_b64_tr_b16 v[176:177], v218 offset:38144
	ds_read_b64_tr_b16 v[174:175], v218 offset:37120
	ds_read_b64_tr_b16 v[178:179], v218 offset:38912
	ds_read_b64_tr_b16 v[180:181], v218 offset:39936
	ds_read_b64_tr_b16 v[184:185], v218 offset:40192
	ds_read_b64_tr_b16 v[182:183], v218 offset:39168
	ds_read_b64_tr_b16 v[186:187], v218 offset:40960
	ds_read_b64_tr_b16 v[188:189], v218 offset:41984
	ds_read_b64_tr_b16 v[192:193], v218 offset:42240
	ds_read_b64_tr_b16 v[190:191], v218 offset:41216
	v_cvt_pk_bf16_f32 v194, v32, v33
	v_cvt_pk_bf16_f32 v195, v34, v35
	v_cvt_pk_bf16_f32 v196, v36, v37
	v_cvt_pk_bf16_f32 v197, v38, v39
	s_andn2_b64 vcc, exec, s[8:9]
	s_waitcnt lgkmcnt(14)
	v_mfma_f32_32x32x16_bf16 v[16:31], v[146:149], v[194:197], v[16:31]
	v_add_f32_e32 v228, v32, v33
	v_add_f32_e32 v229, v48, v49
	v_add_f32_e32 v228, v34, v228
	v_add_f32_e32 v229, v50, v229
	v_cvt_pk_bf16_f32 v146, v48, v49
	v_cvt_pk_bf16_f32 v147, v50, v51
	v_cvt_pk_bf16_f32 v148, v52, v53
	v_cvt_pk_bf16_f32 v149, v54, v55
	s_waitcnt lgkmcnt(12)
	v_mfma_f32_32x32x16_bf16 v[0:15], v[166:169], v[194:197], v[0:15]
	v_add_f32_e32 v228, v35, v228
	v_add_f32_e32 v229, v51, v229
	v_add_f32_e32 v228, v36, v228
	v_add_f32_e32 v229, v52, v229
	v_cvt_pk_bf16_f32 v166, v40, v41
	v_cvt_pk_bf16_f32 v167, v42, v43
	v_cvt_pk_bf16_f32 v168, v44, v45
	v_cvt_pk_bf16_f32 v169, v46, v47
	s_waitcnt lgkmcnt(10)
	v_mfma_f32_32x32x16_bf16 v[16:31], v[170:173], v[166:169], v[16:31]
	v_add_f32_e32 v228, v37, v228
	v_add_f32_e32 v229, v53, v229
	v_add_f32_e32 v228, v38, v228
	v_add_f32_e32 v229, v54, v229
	s_waitcnt lgkmcnt(8)
	v_mfma_f32_32x32x16_bf16 v[0:15], v[174:177], v[166:169], v[0:15]
	v_add_f32_e32 v228, v39, v228
	v_add_f32_e32 v229, v55, v229
	v_add_f32_e32 v228, v40, v228
	v_add_f32_e32 v229, v56, v229
	s_waitcnt lgkmcnt(6)
	v_mfma_f32_32x32x16_bf16 v[16:31], v[178:181], v[146:149], v[16:31]
	v_add_f32_e32 v228, v41, v228
	v_add_f32_e32 v229, v57, v229
	v_add_f32_e32 v228, v42, v228
	v_add_f32_e32 v229, v58, v229
	s_waitcnt lgkmcnt(4)
	v_mfma_f32_32x32x16_bf16 v[0:15], v[182:185], v[146:149], v[0:15]
	v_add_f32_e32 v228, v43, v228
	v_add_f32_e32 v229, v59, v229
	v_add_f32_e32 v228, v44, v228
	v_add_f32_e32 v229, v60, v229
	v_cvt_pk_bf16_f32 v146, v56, v57
	v_cvt_pk_bf16_f32 v147, v58, v59
	v_cvt_pk_bf16_f32 v148, v60, v61
	v_cvt_pk_bf16_f32 v149, v62, v63
	s_waitcnt lgkmcnt(2)
	v_mfma_f32_32x32x16_bf16 v[16:31], v[186:189], v[146:149], v[16:31]
	v_add_f32_e32 v228, v45, v228
	v_add_f32_e32 v229, v61, v229
	v_add_f32_e32 v228, v46, v228
	v_add_f32_e32 v229, v62, v229
	s_waitcnt lgkmcnt(0)
	v_mfma_f32_32x32x16_bf16 v[0:15], v[190:193], v[146:149], v[0:15]
	v_add_f32_e32 v228, v47, v228
	v_add_f32_e32 v229, v63, v229
	v_add_f32_e32 v228, v228, v229
	s_cbranch_vccnz .LBB0_549
	s_add_i32 s13, s10, 2
	s_cmp_ge_u32 s11, s13
	s_cbranch_scc1 .Lmla_w1_tail
	s_waitcnt vmcnt(5)
	ds_write_b128 v220, v[88:91]
	s_waitcnt vmcnt(4)
	ds_write_b128 v219, v[92:95] offset:13312
	s_waitcnt vmcnt(3)
	ds_write_b64 v129, v[116:117] offset:128
	s_branch .LBB0_549
